# GEMM tile loops: per-tile coordinate division replaced by shift/and when the swizzle group height is at its maximum (scalar chain on the leading half's critical path shortened)
# speedup vs baseline: 1.0056x; 1.0056x over previous
.LBB0_437:
	s_ashr_i32 s53, s53, 3
	s_add_i32 s53, s57, s53
	s_ashr_i32 s54, s53, 31
	s_lshr_b32 s54, s54, 26
	s_add_i32 s54, s53, s54
	s_ashr_i32 s55, s54, 6
	s_lshl_b32 s55, s55, 2
	s_sub_i32 s56, 0x100, s55
	s_min_i32 s56, s56, 4
	s_cmp_eq_u32 s56, 4
	s_cbranch_scc0 .Lhdr_slow_1
	s_andn2_b32 s54, s54, 63
	s_sub_i32 s53, s53, s54
	s_lshr_b32 s54, s53, 2
	s_and_b32 s53, s53, 3
	s_add_i32 s56, s55, s53
	s_branch .LBB0_438
.Lhdr_slow_1:
	s_abs_i32 s57, s56
	v_cvt_f32_u32_e32 v0, s57
	s_sub_i32 s59, 0, s57
	s_andn2_b32 s54, s54, 63
	s_sub_i32 s53, s53, s54
	v_rcp_iflag_f32_e32 v0, v0
	s_abs_i32 s54, s53
	s_xor_b32 s58, s53, s56
	s_ashr_i32 s58, s58, 31
	v_mul_f32_e32 v0, 0x4f7ffffe, v0
	v_cvt_u32_f32_e32 v0, v0
	s_nop 0
	v_readfirstlane_b32 s60, v0
	s_mul_i32 s59, s59, s60
	s_mul_hi_u32 s59, s60, s59
	s_add_i32 s60, s60, s59
	s_mul_hi_u32 s59, s54, s60
	s_mul_i32 s60, s59, s57
	s_sub_i32 s54, s54, s60
	s_add_i32 s61, s59, 1
	s_sub_i32 s60, s54, s57
	s_cmp_ge_u32 s54, s57
	s_cselect_b32 s59, s61, s59
	s_cselect_b32 s54, s60, s54
	s_add_i32 s60, s59, 1
	s_cmp_ge_u32 s54, s57
	s_cselect_b32 s54, s60, s59
	s_xor_b32 s54, s54, s58
	s_sub_i32 s54, s54, s58
	s_mul_i32 s56, s54, s56
	s_sub_i32 s53, s53, s56
	s_add_i32 s56, s55, s53

.LBB0_502:
	s_ashr_i32 s36, s38, 3
	s_add_i32 s36, s40, s36
	s_ashr_i32 s37, s36, 31
	s_lshr_b32 s37, s37, 27
	s_add_i32 s37, s36, s37
	s_ashr_i32 s38, s37, 5
	s_lshl_b32 s38, s38, 3
	s_sub_i32 s39, 0x100, s38
	s_min_i32 s39, s39, 8
	s_cmp_eq_u32 s39, 8
	s_cbranch_scc0 .Lhdr_slow_2
	s_andn2_b32 s37, s37, 31
	s_sub_i32 s37, s36, s37
	s_lshr_b32 s36, s37, 3
	s_and_b32 s37, s37, 7
	s_add_i32 s38, s38, s37
	s_branch .LBB0_503
.Lhdr_slow_2:
	s_abs_i32 s40, s39
	v_cvt_f32_u32_e32 v0, s40
	s_sub_i32 s42, 0, s40
	s_andn2_b32 s37, s37, 31
	s_sub_i32 s37, s36, s37
	v_rcp_iflag_f32_e32 v0, v0
	s_abs_i32 s36, s37
	s_xor_b32 s41, s37, s39
	s_ashr_i32 s41, s41, 31
	v_mul_f32_e32 v0, 0x4f7ffffe, v0
	v_cvt_u32_f32_e32 v0, v0
	s_nop 0
	v_readfirstlane_b32 s43, v0
	s_mul_i32 s42, s42, s43
	s_mul_hi_u32 s42, s43, s42
	s_add_i32 s43, s43, s42
	s_mul_hi_u32 s42, s36, s43
	s_mul_i32 s43, s42, s40
	s_sub_i32 s36, s36, s43
	s_add_i32 s45, s42, 1
	s_sub_i32 s43, s36, s40
	s_cmp_ge_u32 s36, s40
	s_cselect_b32 s42, s45, s42
	s_cselect_b32 s36, s43, s36
	s_add_i32 s43, s42, 1
	s_cmp_ge_u32 s36, s40
	s_cselect_b32 s36, s43, s42
	s_xor_b32 s36, s36, s41
	s_sub_i32 s36, s36, s41
	s_mul_i32 s39, s36, s39
	s_sub_i32 s37, s37, s39
	s_add_i32 s38, s38, s37

.LBB0_549:
	s_add_i32 s12, s12, 1
	s_mul_i32 s6, s12, s90
	s_mul_hi_u32 s7, s12, s33
	s_add_i32 s7, s7, s6
	s_mul_i32 s6, s12, s33
	s_add_u32 s58, s6, s2
	s_addc_u32 s59, s7, s91
	v_cmp_gt_i64_e32 vcc, s[58:59], v[158:159]
	v_cmp_lt_i64_e64 s[6:7], s[58:59], v[156:157]
	s_cbranch_vccnz .LBB0_551
	s_ashr_i32 s9, s58, 31
	s_lshr_b32 s9, s9, 29
	s_add_i32 s9, s58, s9
	s_ashr_i32 s11, s9, 3
	s_and_b32 s9, s9, -8
	s_sub_i32 s9, s58, s9
	s_cmp_lt_i32 s9, 0
	s_movk_i32 s13, 0xa1
	s_cselect_b32 s13, s13, 0xa0
	s_mul_i32 s9, s9, s13
	s_add_i32 s9, s9, s11
	s_mul_hi_i32 s11, s9, 0x66666667
	s_lshr_b32 s13, s11, 31
	s_ashr_i32 s11, s11, 4
	s_add_i32 s11, s11, s13
	s_lshl_b32 s13, s11, 3
	s_sub_i32 s16, 0x100, s13
	s_min_i32 s16, s16, 8
	s_cmp_eq_u32 s16, 8
	s_cbranch_scc0 .Lhdr_slow_3
	s_waitcnt lgkmcnt(0)
	s_mul_i32 s11, s11, 40
	s_sub_i32 s9, s9, s11
	s_lshr_b32 s54, s9, 3
	s_and_b32 s9, s9, 7
	s_add_i32 s56, s13, s9
	s_branch .LBB0_551
.Lhdr_slow_3:
	s_abs_i32 s22, s16
	s_waitcnt lgkmcnt(0)
	v_cvt_f32_u32_e32 v0, s22
	s_sub_i32 s54, 0, s22
	s_mul_i32 s11, s11, 40
	s_sub_i32 s9, s9, s11
	v_rcp_iflag_f32_e32 v0, v0
	s_abs_i32 s11, s9
	s_xor_b32 s23, s9, s16
	s_ashr_i32 s23, s23, 31
	v_mul_f32_e32 v0, 0x4f7ffffe, v0
	v_cvt_u32_f32_e32 v0, v0
	s_nop 0
	v_readfirstlane_b32 s55, v0
	s_mul_i32 s54, s54, s55
	s_mul_hi_u32 s54, s55, s54
	s_add_i32 s55, s55, s54
	s_mul_hi_u32 s54, s11, s55
	s_mul_i32 s55, s54, s22
	s_sub_i32 s11, s11, s55
	s_add_i32 s56, s54, 1
	s_sub_i32 s55, s11, s22
	s_cmp_ge_u32 s11, s22
	s_cselect_b32 s54, s56, s54
	s_cselect_b32 s11, s55, s11
	s_add_i32 s55, s54, 1
	s_cmp_ge_u32 s11, s22
	s_cselect_b32 s11, s55, s54
	s_xor_b32 s11, s11, s23
	s_sub_i32 s54, s11, s23
	s_mul_i32 s11, s54, s16
	s_sub_i32 s9, s9, s11
	s_add_i32 s56, s13, s9

.LBB0_742:
	s_ashr_i32 s30, s34, 3
	s_add_i32 s30, s36, s30
	s_ashr_i32 s31, s30, 31
	s_lshr_b32 s31, s31, 27
	s_add_i32 s31, s30, s31
	s_ashr_i32 s34, s31, 5
	s_lshl_b32 s34, s34, 3
	s_sub_i32 s35, 0x100, s34
	s_min_i32 s35, s35, 8
	s_cmp_eq_u32 s35, 8
	s_cbranch_scc0 .Lhdr_slow_4
	s_andn2_b32 s31, s31, 31
	s_sub_i32 s31, s30, s31
	s_lshr_b32 s30, s31, 3
	s_and_b32 s31, s31, 7
	s_add_i32 s34, s34, s31
	s_branch .LBB0_743
.Lhdr_slow_4:
	s_abs_i32 s36, s35
	v_cvt_f32_u32_e32 v0, s36
	s_sub_i32 s38, 0, s36
	s_andn2_b32 s31, s31, 31
	s_sub_i32 s31, s30, s31
	v_rcp_iflag_f32_e32 v0, v0
	s_abs_i32 s30, s31
	s_xor_b32 s37, s31, s35
	s_ashr_i32 s37, s37, 31
	v_mul_f32_e32 v0, 0x4f7ffffe, v0
	v_cvt_u32_f32_e32 v0, v0
	s_nop 0
	v_readfirstlane_b32 s39, v0
	s_mul_i32 s38, s38, s39
	s_mul_hi_u32 s38, s39, s38
	s_add_i32 s39, s39, s38
	s_mul_hi_u32 s38, s30, s39
	s_mul_i32 s39, s38, s36
	s_sub_i32 s30, s30, s39
	s_add_i32 s44, s38, 1
	s_sub_i32 s39, s30, s36
	s_cmp_ge_u32 s30, s36
	s_cselect_b32 s38, s44, s38
	s_cselect_b32 s30, s39, s30
	s_add_i32 s39, s38, 1
	s_cmp_ge_u32 s30, s36
	s_cselect_b32 s30, s39, s38
	s_xor_b32 s30, s30, s37
	s_sub_i32 s30, s30, s37
	s_mul_i32 s35, s30, s35
	s_sub_i32 s31, s31, s35
	s_add_i32 s34, s34, s31

.LBB0_764:
	s_add_i32 s47, s47, 1
	s_mul_i32 s4, s47, s0
	s_mul_hi_u32 s5, s47, s33
	s_add_i32 s5, s5, s4
	s_mul_i32 s4, s47, s33
	s_add_u32 s4, s4, s2
	s_addc_u32 s5, s5, s1
	v_cmp_gt_i64_e32 vcc, s[4:5], v[168:169]
	v_cmp_lt_i64_e64 s[6:7], s[4:5], v[166:167]
	s_cbranch_vccnz .LBB0_766
	s_ashr_i32 s5, s4, 31
	s_lshr_b32 s5, s5, 29
	s_add_i32 s5, s4, s5
	s_ashr_i32 s34, s5, 3
	s_and_b32 s5, s5, -8
	s_sub_i32 s4, s4, s5
	s_cmp_lt_i32 s4, 0
	s_cselect_b32 s5, s59, 0x60
	s_mul_i32 s4, s4, s5
	s_add_i32 s4, s4, s34
	s_mul_hi_i32 s5, s4, 0x2aaaaaab
	s_lshr_b32 s34, s5, 31
	s_ashr_i32 s5, s5, 2
	s_add_i32 s5, s5, s34
	s_lshl_b32 s34, s5, 3
	s_sub_i32 s35, 0x100, s34
	s_min_i32 s35, s35, 8
	s_cmp_eq_u32 s35, 8
	s_cbranch_scc0 .Lhdr_slow_5
	s_mul_i32 s5, s5, 24
	s_sub_i32 s4, s4, s5
	s_lshr_b32 s74, s4, 3
	s_and_b32 s4, s4, 7
	s_add_i32 s75, s34, s4
	s_branch .LBB0_766
.Lhdr_slow_5:
	s_abs_i32 s36, s35
	v_cvt_f32_u32_e32 v0, s36
	s_sub_i32 s40, 0, s36
	s_mul_i32 s5, s5, 24
	s_sub_i32 s4, s4, s5
	v_rcp_iflag_f32_e32 v0, v0
	s_abs_i32 s5, s4
	s_xor_b32 s37, s4, s35
	s_ashr_i32 s37, s37, 31
	v_mul_f32_e32 v0, 0x4f7ffffe, v0
	v_cvt_u32_f32_e32 v0, v0
	s_nop 0
	v_readfirstlane_b32 s41, v0
	s_mul_i32 s40, s40, s41
	s_mul_hi_u32 s40, s41, s40
	s_add_i32 s41, s41, s40
	s_mul_hi_u32 s40, s5, s41
	s_mul_i32 s41, s40, s36
	s_sub_i32 s5, s5, s41
	s_add_i32 s74, s40, 1
	s_sub_i32 s41, s5, s36
	s_cmp_ge_u32 s5, s36
	s_cselect_b32 s40, s74, s40
	s_cselect_b32 s5, s41, s5
	s_add_i32 s41, s40, 1
	s_cmp_ge_u32 s5, s36
	s_cselect_b32 s5, s41, s40
	s_xor_b32 s5, s5, s37
	s_sub_i32 s74, s5, s37
	s_mul_i32 s5, s74, s35
	s_sub_i32 s4, s4, s5
	s_add_i32 s75, s34, s4

.LBB0_936:
	s_ashr_i32 s9, s9, 3
	s_add_i32 s9, s27, s9
	s_ashr_i32 s22, s9, 31
	s_lshr_b32 s22, s22, 27
	s_add_i32 s22, s9, s22
	s_ashr_i32 s23, s22, 5
	s_lshl_b32 s23, s23, 3
	s_sub_i32 s26, 0x100, s23
	s_min_i32 s26, s26, 8
	s_cmp_eq_u32 s26, 8
	s_cbranch_scc0 .Lhdr_slow_6
	s_andn2_b32 s22, s22, 31
	s_sub_i32 s9, s9, s22
	s_lshr_b32 s22, s9, 3
	s_and_b32 s9, s9, 7
	s_add_i32 s26, s23, s9
	s_branch .LBB0_937
.Lhdr_slow_6:
	s_abs_i32 s27, s26
	v_cvt_f32_u32_e32 v0, s27
	s_sub_i32 s29, 0, s27
	s_andn2_b32 s22, s22, 31
	s_sub_i32 s9, s9, s22
	v_rcp_iflag_f32_e32 v0, v0
	s_abs_i32 s22, s9
	s_xor_b32 s28, s9, s26
	s_ashr_i32 s28, s28, 31
	v_mul_f32_e32 v0, 0x4f7ffffe, v0
	v_cvt_u32_f32_e32 v0, v0
	s_nop 0
	v_readfirstlane_b32 s30, v0
	s_mul_i32 s29, s29, s30
	s_mul_hi_u32 s29, s30, s29
	s_add_i32 s30, s30, s29
	s_mul_hi_u32 s29, s22, s30
	s_mul_i32 s30, s29, s27
	s_sub_i32 s22, s22, s30
	s_add_i32 s31, s29, 1
	s_sub_i32 s30, s22, s27
	s_cmp_ge_u32 s22, s27
	s_cselect_b32 s29, s31, s29
	s_cselect_b32 s22, s30, s22
	s_add_i32 s30, s29, 1
	s_cmp_ge_u32 s22, s27
	s_cselect_b32 s22, s30, s29
	s_xor_b32 s22, s22, s28
	s_sub_i32 s22, s22, s28
	s_mul_i32 s26, s22, s26
	s_sub_i32 s9, s9, s26
	s_add_i32 s26, s23, s9
